# static s_setprio 1 for waves 0-3 (other half) before each GEMM K-loop, flips removed
# baseline (speedup 1.0000x reference)
; template <class Epi>
; DI void gemm_phase(LAS unsigned char* lds, const Gemm g, const StaticOrder& S, const Epi& E) {
;     ...
;         const bool has_next = S.next(ui + 1, nxt);
;         const char* nA = has_next ? (const char*)g.A + (size_t)nxt.pm * tstep : cA; const char* nB = has_next ? (const char*)g.Bt + (size_t)nxt.pn * tstep : cB;
;     ...
;         for (int a = 0; a < 2; ++a)
; #pragma unroll
;             for (int b = 0; b < 2; ++b)
; #pragma unroll
;                 for (int m = 0; m < 4; ++m)
; #pragma unroll
;                     for (int n = 0; n < 2; ++n) acc[a][b][m][n] = (f32x4){0.f, 0.f, 0.f, 0.f};
.LBB0_91:
	s_ashr_i32 s55, s54, 31
	s_lshl_b64 s[22:23], s[54:55], 19
	s_add_u32 s56, s24, s22
	s_addc_u32 s57, s25, s23
	s_and_b64 s[22:23], s[4:5], exec
	s_cselect_b32 s7, s57, s65
	s_cselect_b32 s17, s56, s64
	s_ashr_i32 s53, s52, 31
	s_lshl_b64 s[22:23], s[52:53], 19
	s_add_u32 s58, s30, s22
	s_addc_u32 s59, s31, s23
	s_and_b64 s[22:23], s[4:5], exec
	s_cselect_b32 s22, s59, s63
	s_cselect_b32 s23, s58, s62
	s_add_u32 s42, s62, 0x100
	s_addc_u32 s43, s63, 0
	s_add_u32 s62, s64, 0x40080
	v_mov_b32_e32 v2, 0
	s_addc_u32 s63, s65, 0
	s_mov_b32 s53, -2
	v_mov_b32_e32 v3, v2
	v_mov_b32_e32 v4, v2
	v_mov_b32_e32 v5, v2
	v_mov_b32_e32 v6, v2
	v_mov_b32_e32 v7, v2
	v_mov_b32_e32 v8, v2
	v_mov_b32_e32 v9, v2
	v_mov_b32_e32 v18, v2
	v_mov_b32_e32 v19, v2
	v_mov_b32_e32 v20, v2
	v_mov_b32_e32 v21, v2
	v_mov_b32_e32 v22, v2
	v_mov_b32_e32 v23, v2
	v_mov_b32_e32 v24, v2
	v_mov_b32_e32 v25, v2
	v_mov_b32_e32 v34, v2
	v_mov_b32_e32 v35, v2
	v_mov_b32_e32 v36, v2
	v_mov_b32_e32 v37, v2
	v_mov_b32_e32 v38, v2
	v_mov_b32_e32 v39, v2
	v_mov_b32_e32 v40, v2
	v_mov_b32_e32 v41, v2
	v_mov_b32_e32 v50, v2
	v_mov_b32_e32 v51, v2
	v_mov_b32_e32 v52, v2
	v_mov_b32_e32 v53, v2
	v_mov_b32_e32 v54, v2
	v_mov_b32_e32 v55, v2
	v_mov_b32_e32 v56, v2
	v_mov_b32_e32 v57, v2
	v_mov_b32_e32 v10, v2
	v_mov_b32_e32 v11, v2
	v_mov_b32_e32 v12, v2
	v_mov_b32_e32 v13, v2
	v_mov_b32_e32 v14, v2
	v_mov_b32_e32 v15, v2
	v_mov_b32_e32 v16, v2
	v_mov_b32_e32 v17, v2
	v_mov_b32_e32 v26, v2
	v_mov_b32_e32 v27, v2
	v_mov_b32_e32 v28, v2
	v_mov_b32_e32 v29, v2
	v_mov_b32_e32 v30, v2
	v_mov_b32_e32 v31, v2
	v_mov_b32_e32 v32, v2
	v_mov_b32_e32 v33, v2
	v_mov_b32_e32 v42, v2
	v_mov_b32_e32 v43, v2
	v_mov_b32_e32 v44, v2
	v_mov_b32_e32 v45, v2
	v_mov_b32_e32 v46, v2
	v_mov_b32_e32 v47, v2
	v_mov_b32_e32 v48, v2
	v_mov_b32_e32 v49, v2
	v_mov_b32_e32 v58, v2
	v_mov_b32_e32 v59, v2
	v_mov_b32_e32 v60, v2
	v_mov_b32_e32 v61, v2
	v_mov_b32_e32 v62, v2
	v_mov_b32_e32 v63, v2
	v_mov_b32_e32 v64, v2
	v_mov_b32_e32 v65, v2
	s_waitcnt vmcnt(0)
	v_mov_b32_e32 v70, v2
	v_mov_b32_e32 v71, v2
	v_mov_b32_e32 v72, v2
	v_mov_b32_e32 v73, v2
	v_mov_b32_e32 v74, v2
	v_mov_b32_e32 v75, v2
	v_mov_b32_e32 v76, v2
	v_mov_b32_e32 v77, v2
	v_mov_b32_e32 v90, v2
	v_mov_b32_e32 v91, v2
	v_mov_b32_e32 v92, v2
	v_mov_b32_e32 v93, v2
	v_mov_b32_e32 v94, v2
	v_mov_b32_e32 v95, v2
	v_mov_b32_e32 v96, v2
	v_mov_b32_e32 v97, v2
	v_mov_b32_e32 v110, v2
	v_mov_b32_e32 v111, v2
	v_mov_b32_e32 v112, v2
	v_mov_b32_e32 v113, v2
	v_mov_b32_e32 v114, v2
	v_mov_b32_e32 v115, v2
	v_mov_b32_e32 v116, v2
	v_mov_b32_e32 v117, v2
	v_mov_b32_e32 v130, v2
	v_mov_b32_e32 v131, v2
	v_mov_b32_e32 v132, v2
	v_mov_b32_e32 v133, v2
	v_mov_b32_e32 v134, v2
	v_mov_b32_e32 v135, v2
	v_mov_b32_e32 v136, v2
	v_mov_b32_e32 v137, v2
	v_mov_b32_e32 v82, v2
	v_mov_b32_e32 v83, v2
	v_mov_b32_e32 v84, v2
	v_mov_b32_e32 v85, v2
	v_mov_b32_e32 v86, v2
	v_mov_b32_e32 v87, v2
	v_mov_b32_e32 v88, v2
	v_mov_b32_e32 v89, v2
	v_mov_b32_e32 v102, v2
	v_mov_b32_e32 v103, v2
	v_mov_b32_e32 v104, v2
	v_mov_b32_e32 v105, v2
	v_mov_b32_e32 v106, v2
	v_mov_b32_e32 v107, v2
	v_mov_b32_e32 v108, v2
	v_mov_b32_e32 v109, v2
	v_mov_b32_e32 v122, v2
	v_mov_b32_e32 v123, v2
	v_mov_b32_e32 v124, v2
	v_mov_b32_e32 v125, v2
	v_mov_b32_e32 v126, v2
	v_mov_b32_e32 v127, v2
	v_mov_b32_e32 v128, v2
	v_mov_b32_e32 v129, v2
	v_mov_b32_e32 v146, v2
	v_mov_b32_e32 v147, v2
	v_mov_b32_e32 v148, v2
	v_mov_b32_e32 v149, v2
	v_mov_b32_e32 v150, v2
	v_mov_b32_e32 v151, v2
	v_mov_b32_e32 v152, v2
	v_mov_b32_e32 v153, v2
	v_readfirstlane_b32 s101, v242
	s_nop 3
	s_lshr_b32 s101, s101, 8
	s_cmp_eq_u32 s101, 0
	s_cbranch_scc0 .Lsp_5
	s_setprio 1

; template <class Epi>
; DI void gemm_phase(LAS unsigned char* lds, const Gemm g, const StaticOrder& S, const Epi& E) {
;     ...
;         const bool has_next = S.next(ui + 1, nxt);
;         const char* nA = has_next ? (const char*)g.A + (size_t)nxt.pm * tstep : cA; const char* nB = has_next ? (const char*)g.Bt + (size_t)nxt.pn * tstep : cB;
;     ...
;         for (int a = 0; a < 2; ++a)
; #pragma unroll
;             for (int b = 0; b < 2; ++b)
; #pragma unroll
;                 for (int m = 0; m < 4; ++m)
; #pragma unroll
;                     for (int n = 0; n < 2; ++n) acc[a][b][m][n] = (f32x4){0.f, 0.f, 0.f, 0.f};
.LBB0_514:
	s_ashr_i32 s57, s56, 31
	s_lshl_b64 s[22:23], s[56:57], 19
	s_add_u32 s58, s72, s22
	s_addc_u32 s59, s73, s23
	s_and_b64 s[22:23], s[4:5], exec
	s_cselect_b32 s22, s59, s67
	s_cselect_b32 s23, s58, s66
	s_ashr_i32 s55, s54, 31
	s_lshl_b64 s[42:43], s[54:55], 19
	s_add_u32 s60, s95, s42
	s_addc_u32 s61, s30, s43
	s_and_b64 s[42:43], s[4:5], exec
	s_cselect_b32 s42, s61, s65
	s_cselect_b32 s43, s60, s64
	s_add_u32 s55, s64, 0x100
	s_addc_u32 s57, s65, 0
	s_add_u32 s64, s66, 0x40080
	v_mov_b32_e32 v2, 0
	s_addc_u32 s65, s67, 0
	s_mov_b32 s63, -2
	v_mov_b32_e32 v3, v2
	v_mov_b32_e32 v4, v2
	v_mov_b32_e32 v5, v2
	v_mov_b32_e32 v6, v2
	v_mov_b32_e32 v7, v2
	v_mov_b32_e32 v8, v2
	v_mov_b32_e32 v9, v2
	v_mov_b32_e32 v18, v2
	v_mov_b32_e32 v19, v2
	v_mov_b32_e32 v20, v2
	v_mov_b32_e32 v21, v2
	v_mov_b32_e32 v22, v2
	v_mov_b32_e32 v23, v2
	v_mov_b32_e32 v24, v2
	v_mov_b32_e32 v25, v2
	v_mov_b32_e32 v34, v2
	v_mov_b32_e32 v35, v2
	v_mov_b32_e32 v36, v2
	v_mov_b32_e32 v37, v2
	v_mov_b32_e32 v38, v2
	v_mov_b32_e32 v39, v2
	v_mov_b32_e32 v40, v2
	v_mov_b32_e32 v41, v2
	v_mov_b32_e32 v66, v2
	v_mov_b32_e32 v67, v2
	v_mov_b32_e32 v68, v2
	v_mov_b32_e32 v69, v2
	v_mov_b32_e32 v70, v2
	v_mov_b32_e32 v71, v2
	v_mov_b32_e32 v72, v2
	v_mov_b32_e32 v73, v2
	v_mov_b32_e32 v10, v2
	v_mov_b32_e32 v11, v2
	v_mov_b32_e32 v12, v2
	v_mov_b32_e32 v13, v2
	v_mov_b32_e32 v14, v2
	v_mov_b32_e32 v15, v2
	v_mov_b32_e32 v16, v2
	v_mov_b32_e32 v17, v2
	v_mov_b32_e32 v26, v2
	v_mov_b32_e32 v27, v2
	v_mov_b32_e32 v28, v2
	v_mov_b32_e32 v29, v2
	v_mov_b32_e32 v30, v2
	v_mov_b32_e32 v31, v2
	v_mov_b32_e32 v32, v2
	v_mov_b32_e32 v33, v2
	v_mov_b32_e32 v50, v2
	v_mov_b32_e32 v51, v2
	v_mov_b32_e32 v52, v2
	v_mov_b32_e32 v53, v2
	v_mov_b32_e32 v54, v2
	v_mov_b32_e32 v55, v2
	v_mov_b32_e32 v56, v2
	v_mov_b32_e32 v57, v2
	v_mov_b32_e32 v74, v2
	v_mov_b32_e32 v75, v2
	v_mov_b32_e32 v76, v2
	v_mov_b32_e32 v77, v2
	v_mov_b32_e32 v78, v2
	v_mov_b32_e32 v79, v2
	v_mov_b32_e32 v80, v2
	v_mov_b32_e32 v81, v2
	v_mov_b32_e32 v82, v2
	v_mov_b32_e32 v83, v2
	v_mov_b32_e32 v84, v2
	v_mov_b32_e32 v85, v2
	v_mov_b32_e32 v86, v2
	v_mov_b32_e32 v87, v2
	v_mov_b32_e32 v88, v2
	v_mov_b32_e32 v89, v2
	v_mov_b32_e32 v98, v2
	v_mov_b32_e32 v99, v2
	v_mov_b32_e32 v100, v2
	v_mov_b32_e32 v101, v2
	v_mov_b32_e32 v102, v2
	v_mov_b32_e32 v103, v2
	v_mov_b32_e32 v104, v2
	v_mov_b32_e32 v105, v2
	v_mov_b32_e32 v114, v2
	v_mov_b32_e32 v115, v2
	v_mov_b32_e32 v116, v2
	v_mov_b32_e32 v117, v2
	v_mov_b32_e32 v118, v2
	v_mov_b32_e32 v119, v2
	v_mov_b32_e32 v120, v2
	v_mov_b32_e32 v121, v2
	v_mov_b32_e32 v130, v2
	v_mov_b32_e32 v131, v2
	v_mov_b32_e32 v132, v2
	v_mov_b32_e32 v133, v2
	v_mov_b32_e32 v134, v2
	v_mov_b32_e32 v135, v2
	v_mov_b32_e32 v136, v2
	v_mov_b32_e32 v137, v2
	v_mov_b32_e32 v90, v2
	v_mov_b32_e32 v91, v2
	v_mov_b32_e32 v92, v2
	v_mov_b32_e32 v93, v2
	v_mov_b32_e32 v94, v2
	v_mov_b32_e32 v95, v2
	v_mov_b32_e32 v96, v2
	v_mov_b32_e32 v97, v2
	v_mov_b32_e32 v106, v2
	v_mov_b32_e32 v107, v2
	v_mov_b32_e32 v108, v2
	v_mov_b32_e32 v109, v2
	v_mov_b32_e32 v110, v2
	v_mov_b32_e32 v111, v2
	v_mov_b32_e32 v112, v2
	v_mov_b32_e32 v113, v2
	v_mov_b32_e32 v122, v2
	v_mov_b32_e32 v123, v2
	v_mov_b32_e32 v124, v2
	v_mov_b32_e32 v125, v2
	v_mov_b32_e32 v126, v2
	v_mov_b32_e32 v127, v2
	v_mov_b32_e32 v128, v2
	v_mov_b32_e32 v129, v2
	v_mov_b32_e32 v146, v2
	v_mov_b32_e32 v147, v2
	v_mov_b32_e32 v148, v2
	v_mov_b32_e32 v149, v2
	v_mov_b32_e32 v150, v2
	v_mov_b32_e32 v151, v2
	v_mov_b32_e32 v152, v2
	v_mov_b32_e32 v153, v2
	v_readfirstlane_b32 s101, v242
	s_nop 3
	s_lshr_b32 s101, s101, 8
	s_cmp_eq_u32 s101, 0
	s_cbranch_scc0 .Lsp_4
	s_setprio 1

; template <class Epi>
; DI void gemm_phase(LAS unsigned char* lds, const Gemm g, const StaticOrder& S, const Epi& E) {
;     ...
;         const bool has_next = S.next(ui + 1, nxt);
;         const char* nA = has_next ? (const char*)g.A + (size_t)nxt.pm * tstep : cA; const char* nB = has_next ? (const char*)g.Bt + (size_t)nxt.pn * tstep : cB;
;     ...
;         for (int a = 0; a < 2; ++a)
; #pragma unroll
;             for (int b = 0; b < 2; ++b)
; #pragma unroll
;                 for (int m = 0; m < 4; ++m)
; #pragma unroll
;                     for (int n = 0; n < 2; ++n) acc[a][b][m][n] = (f32x4){0.f, 0.f, 0.f, 0.f};
.LBB0_538:
	s_ashr_i32 s59, s58, 31
	s_lshl_b64 s[60:61], s[58:59], 18
	s_add_u32 s60, s30, s60
	s_addc_u32 s61, s31, s61
	s_and_b64 s[62:63], s[4:5], exec
	s_cselect_b32 s23, s61, s69
	s_cselect_b32 s43, s60, s68
	s_ashr_i32 s57, s56, 31
	s_lshl_b64 s[62:63], s[56:57], 18
	s_add_u32 s62, s36, s62
	s_addc_u32 s63, s37, s63
	s_and_b64 s[70:71], s[4:5], exec
	s_cselect_b32 s57, s63, s67
	s_cselect_b32 s59, s62, s66
	s_add_u32 s94, s66, 0x100
	s_addc_u32 s95, s67, 0
	s_add_u32 s66, s68, 0x20080
	v_mov_b32_e32 v2, 0
	s_addc_u32 s67, s69, 0
	s_mov_b32 vcc_lo, -2
	v_mov_b32_e32 v3, v2
	v_mov_b32_e32 v4, v2
	v_mov_b32_e32 v5, v2
	v_mov_b32_e32 v6, v2
	v_mov_b32_e32 v7, v2
	v_mov_b32_e32 v8, v2
	v_mov_b32_e32 v9, v2
	v_mov_b32_e32 v18, v2
	v_mov_b32_e32 v19, v2
	v_mov_b32_e32 v20, v2
	v_mov_b32_e32 v21, v2
	v_mov_b32_e32 v22, v2
	v_mov_b32_e32 v23, v2
	v_mov_b32_e32 v24, v2
	v_mov_b32_e32 v25, v2
	v_mov_b32_e32 v34, v2
	v_mov_b32_e32 v35, v2
	v_mov_b32_e32 v36, v2
	v_mov_b32_e32 v37, v2
	v_mov_b32_e32 v38, v2
	v_mov_b32_e32 v39, v2
	v_mov_b32_e32 v40, v2
	v_mov_b32_e32 v41, v2
	v_mov_b32_e32 v50, v2
	v_mov_b32_e32 v51, v2
	v_mov_b32_e32 v52, v2
	v_mov_b32_e32 v53, v2
	v_mov_b32_e32 v54, v2
	v_mov_b32_e32 v55, v2
	v_mov_b32_e32 v56, v2
	v_mov_b32_e32 v57, v2
	v_mov_b32_e32 v10, v2
	v_mov_b32_e32 v11, v2
	v_mov_b32_e32 v12, v2
	v_mov_b32_e32 v13, v2
	v_mov_b32_e32 v14, v2
	v_mov_b32_e32 v15, v2
	v_mov_b32_e32 v16, v2
	v_mov_b32_e32 v17, v2
	v_mov_b32_e32 v26, v2
	v_mov_b32_e32 v27, v2
	v_mov_b32_e32 v28, v2
	v_mov_b32_e32 v29, v2
	v_mov_b32_e32 v30, v2
	v_mov_b32_e32 v31, v2
	v_mov_b32_e32 v32, v2
	v_mov_b32_e32 v33, v2
	v_mov_b32_e32 v42, v2
	v_mov_b32_e32 v43, v2
	v_mov_b32_e32 v44, v2
	v_mov_b32_e32 v45, v2
	v_mov_b32_e32 v46, v2
	v_mov_b32_e32 v47, v2
	v_mov_b32_e32 v48, v2
	v_mov_b32_e32 v49, v2
	v_mov_b32_e32 v58, v2
	v_mov_b32_e32 v59, v2
	v_mov_b32_e32 v60, v2
	v_mov_b32_e32 v61, v2
	v_mov_b32_e32 v62, v2
	v_mov_b32_e32 v63, v2
	v_mov_b32_e32 v64, v2
	v_mov_b32_e32 v65, v2
	v_mov_b32_e32 v74, v2
	v_mov_b32_e32 v75, v2
	v_mov_b32_e32 v76, v2
	v_mov_b32_e32 v77, v2
	v_mov_b32_e32 v78, v2
	v_mov_b32_e32 v79, v2
	v_mov_b32_e32 v80, v2
	v_mov_b32_e32 v81, v2
	v_mov_b32_e32 v98, v2
	v_mov_b32_e32 v99, v2
	v_mov_b32_e32 v100, v2
	v_mov_b32_e32 v101, v2
	v_mov_b32_e32 v102, v2
	v_mov_b32_e32 v103, v2
	v_mov_b32_e32 v104, v2
	v_mov_b32_e32 v105, v2
	v_mov_b32_e32 v114, v2
	v_mov_b32_e32 v115, v2
	v_mov_b32_e32 v116, v2
	v_mov_b32_e32 v117, v2
	v_mov_b32_e32 v118, v2
	v_mov_b32_e32 v119, v2
	v_mov_b32_e32 v120, v2
	v_mov_b32_e32 v121, v2
	v_mov_b32_e32 v130, v2
	v_mov_b32_e32 v131, v2
	v_mov_b32_e32 v132, v2
	v_mov_b32_e32 v133, v2
	v_mov_b32_e32 v134, v2
	v_mov_b32_e32 v135, v2
	v_mov_b32_e32 v136, v2
	v_mov_b32_e32 v137, v2
	v_mov_b32_e32 v90, v2
	v_mov_b32_e32 v91, v2
	v_mov_b32_e32 v92, v2
	v_mov_b32_e32 v93, v2
	v_mov_b32_e32 v94, v2
	v_mov_b32_e32 v95, v2
	v_mov_b32_e32 v96, v2
	v_mov_b32_e32 v97, v2
	v_mov_b32_e32 v106, v2
	v_mov_b32_e32 v107, v2
	v_mov_b32_e32 v108, v2
	v_mov_b32_e32 v109, v2
	v_mov_b32_e32 v110, v2
	v_mov_b32_e32 v111, v2
	v_mov_b32_e32 v112, v2
	v_mov_b32_e32 v113, v2
	v_mov_b32_e32 v122, v2
	v_mov_b32_e32 v123, v2
	v_mov_b32_e32 v124, v2
	v_mov_b32_e32 v125, v2
	v_mov_b32_e32 v126, v2
	v_mov_b32_e32 v127, v2
	v_mov_b32_e32 v128, v2
	v_mov_b32_e32 v129, v2
	v_mov_b32_e32 v138, v2
	v_mov_b32_e32 v139, v2
	v_mov_b32_e32 v140, v2
	v_mov_b32_e32 v141, v2
	v_mov_b32_e32 v142, v2
	v_mov_b32_e32 v143, v2
	v_mov_b32_e32 v144, v2
	v_mov_b32_e32 v145, v2
	v_readfirstlane_b32 s101, v242
	s_nop 3
	s_lshr_b32 s101, s101, 8
	s_cmp_eq_u32 s101, 0
	s_cbranch_scc0 .Lsp_3
	s_setprio 1

; template <class Epi>
; DI void gemm_phase(LAS unsigned char* lds, const Gemm g, const StaticOrder& S, const Epi& E) {
;     ...
;         const bool has_next = S.next(ui + 1, nxt);
;         const char* nA = has_next ? (const char*)g.A + (size_t)nxt.pm * tstep : cA; const char* nB = has_next ? (const char*)g.Bt + (size_t)nxt.pn * tstep : cB;
;     ...
;         for (int a = 0; a < 2; ++a)
; #pragma unroll
;             for (int b = 0; b < 2; ++b)
; #pragma unroll
;                 for (int m = 0; m < 4; ++m)
; #pragma unroll
;                     for (int n = 0; n < 2; ++n) acc[a][b][m][n] = (f32x4){0.f, 0.f, 0.f, 0.f};
.LBB0_616:
	s_ashr_i32 s57, s56, 31
	s_lshl_b64 s[18:19], s[56:57], 19
	s_add_u32 s58, s25, s18
	s_addc_u32 s59, s30, s19
	s_and_b64 s[18:19], s[6:7], exec
	s_cselect_b32 s12, s59, s67
	s_cselect_b32 s23, s58, s66
	s_ashr_i32 s55, s54, 31
	s_lshl_b64 s[18:19], s[54:55], 19
	s_add_u32 s60, s31, s18
	s_addc_u32 s61, s36, s19
	s_and_b64 s[18:19], s[6:7], exec
	s_cselect_b32 s55, s61, s69
	s_cselect_b32 s57, s60, s68
	s_add_u32 s63, s68, 0x100
	v_mov_b32_e32 v2, 0
	s_addc_u32 s65, s69, 0
	s_mov_b32 vcc_lo, -2
	s_waitcnt lgkmcnt(0)
	v_mov_b32_e32 v3, v2
	v_mov_b32_e32 v4, v2
	v_mov_b32_e32 v5, v2
	v_mov_b32_e32 v6, v2
	v_mov_b32_e32 v7, v2
	v_mov_b32_e32 v8, v2
	v_mov_b32_e32 v9, v2
	v_mov_b32_e32 v18, v2
	v_mov_b32_e32 v19, v2
	v_mov_b32_e32 v20, v2
	v_mov_b32_e32 v21, v2
	v_mov_b32_e32 v22, v2
	v_mov_b32_e32 v23, v2
	v_mov_b32_e32 v24, v2
	v_mov_b32_e32 v25, v2
	v_mov_b32_e32 v34, v2
	v_mov_b32_e32 v35, v2
	v_mov_b32_e32 v36, v2
	v_mov_b32_e32 v37, v2
	v_mov_b32_e32 v38, v2
	v_mov_b32_e32 v39, v2
	v_mov_b32_e32 v40, v2
	v_mov_b32_e32 v41, v2
	v_mov_b32_e32 v50, v2
	v_mov_b32_e32 v51, v2
	v_mov_b32_e32 v52, v2
	v_mov_b32_e32 v53, v2
	v_mov_b32_e32 v54, v2
	v_mov_b32_e32 v55, v2
	v_mov_b32_e32 v56, v2
	v_mov_b32_e32 v57, v2
	v_mov_b32_e32 v10, v2
	v_mov_b32_e32 v11, v2
	v_mov_b32_e32 v12, v2
	v_mov_b32_e32 v13, v2
	v_mov_b32_e32 v14, v2
	v_mov_b32_e32 v15, v2
	v_mov_b32_e32 v16, v2
	v_mov_b32_e32 v17, v2
	v_mov_b32_e32 v26, v2
	v_mov_b32_e32 v27, v2
	v_mov_b32_e32 v28, v2
	v_mov_b32_e32 v29, v2
	v_mov_b32_e32 v30, v2
	v_mov_b32_e32 v31, v2
	v_mov_b32_e32 v32, v2
	v_mov_b32_e32 v33, v2
	v_mov_b32_e32 v42, v2
	v_mov_b32_e32 v43, v2
	v_mov_b32_e32 v44, v2
	v_mov_b32_e32 v45, v2
	v_mov_b32_e32 v46, v2
	v_mov_b32_e32 v47, v2
	v_mov_b32_e32 v48, v2
	v_mov_b32_e32 v49, v2
	v_mov_b32_e32 v58, v2
	v_mov_b32_e32 v59, v2
	v_mov_b32_e32 v60, v2
	v_mov_b32_e32 v61, v2
	v_mov_b32_e32 v62, v2
	v_mov_b32_e32 v63, v2
	v_mov_b32_e32 v64, v2
	v_mov_b32_e32 v65, v2
	v_mov_b32_e32 v66, v2
	v_mov_b32_e32 v67, v2
	v_mov_b32_e32 v68, v2
	v_mov_b32_e32 v69, v2
	v_mov_b32_e32 v70, v2
	v_mov_b32_e32 v71, v2
	v_mov_b32_e32 v72, v2
	v_mov_b32_e32 v73, v2
	v_mov_b32_e32 v82, v2
	v_mov_b32_e32 v83, v2
	v_mov_b32_e32 v84, v2
	v_mov_b32_e32 v85, v2
	v_mov_b32_e32 v86, v2
	v_mov_b32_e32 v87, v2
	v_mov_b32_e32 v88, v2
	v_mov_b32_e32 v89, v2
	v_mov_b32_e32 v98, v2
	v_mov_b32_e32 v99, v2
	v_mov_b32_e32 v100, v2
	v_mov_b32_e32 v101, v2
	v_mov_b32_e32 v102, v2
	v_mov_b32_e32 v103, v2
	v_mov_b32_e32 v104, v2
	v_mov_b32_e32 v105, v2
	v_mov_b32_e32 v130, v2
	v_mov_b32_e32 v131, v2
	v_mov_b32_e32 v132, v2
	v_mov_b32_e32 v133, v2
	v_mov_b32_e32 v142, v2
	v_mov_b32_e32 v143, v2
	v_mov_b32_e32 v144, v2
	v_mov_b32_e32 v145, v2
	v_mov_b32_e32 v74, v2
	v_mov_b32_e32 v75, v2
	v_mov_b32_e32 v76, v2
	v_mov_b32_e32 v77, v2
	v_mov_b32_e32 v78, v2
	v_mov_b32_e32 v79, v2
	v_mov_b32_e32 v80, v2
	v_mov_b32_e32 v81, v2
	v_mov_b32_e32 v90, v2
	v_mov_b32_e32 v91, v2
	v_mov_b32_e32 v92, v2
	v_mov_b32_e32 v93, v2
	v_mov_b32_e32 v94, v2
	v_mov_b32_e32 v95, v2
	v_mov_b32_e32 v96, v2
	v_mov_b32_e32 v97, v2
	v_mov_b32_e32 v106, v2
	v_mov_b32_e32 v107, v2
	v_mov_b32_e32 v108, v2
	v_mov_b32_e32 v109, v2
	v_mov_b32_e32 v110, v2
	v_mov_b32_e32 v111, v2
	v_mov_b32_e32 v112, v2
	v_mov_b32_e32 v113, v2
	v_mov_b32_e32 v150, v2
	v_mov_b32_e32 v151, v2
	v_mov_b32_e32 v152, v2
	v_mov_b32_e32 v153, v2
	v_mov_b32_e32 v158, v2
	v_mov_b32_e32 v159, v2
	v_mov_b32_e32 v160, v2
	v_mov_b32_e32 v161, v2
	v_readfirstlane_b32 s101, v242
	s_nop 3
	s_lshr_b32 s101, s101, 8
	s_cmp_eq_u32 s101, 0
	s_cbranch_scc0 .Lsp_2
	s_setprio 1

; template <class Epi>
; DI void gemm_phase(LAS unsigned char* lds, const Gemm g, const StaticOrder& S, const Epi& E) {
;     ...
;         const bool has_next = S.next(ui + 1, nxt);
;         const char* nA = has_next ? (const char*)g.A + (size_t)nxt.pm * tstep : cA; const char* nB = has_next ? (const char*)g.Bt + (size_t)nxt.pn * tstep : cB;
;     ...
;         for (int a = 0; a < 2; ++a)
; #pragma unroll
;             for (int b = 0; b < 2; ++b)
; #pragma unroll
;                 for (int m = 0; m < 4; ++m)
; #pragma unroll
;                     for (int n = 0; n < 2; ++n) acc[a][b][m][n] = (f32x4){0.f, 0.f, 0.f, 0.f};
.LBB0_700:
	s_ashr_i32 s49, s48, 31
	s_lshl_b64 s[18:19], s[48:49], 19
	s_add_u32 s50, s25, s18
	s_addc_u32 s51, s30, s19
	s_and_b64 s[18:19], s[4:5], exec
	s_cselect_b32 s22, s51, s59
	s_cselect_b32 s23, s50, s58
	s_ashr_i32 s47, s46, 31
	s_lshl_b64 s[18:19], s[46:47], 19
	s_add_u32 s52, s31, s18
	s_addc_u32 s53, s36, s19
	s_and_b64 s[18:19], s[4:5], exec
	s_cselect_b32 s42, s53, s57
	s_cselect_b32 s43, s52, s56
	s_add_u32 s47, s56, 0x100
	s_addc_u32 s49, s57, 0
	s_add_u32 s56, s58, 0x40080
	v_mov_b32_e32 v2, 0
	s_addc_u32 s57, s59, 0
	s_mov_b32 s68, -2
	v_mov_b32_e32 v3, v2
	v_mov_b32_e32 v4, v2
	v_mov_b32_e32 v5, v2
	v_mov_b32_e32 v10, v2
	v_mov_b32_e32 v11, v2
	v_mov_b32_e32 v12, v2
	v_mov_b32_e32 v13, v2
	v_mov_b32_e32 v18, v2
	v_mov_b32_e32 v19, v2
	v_mov_b32_e32 v20, v2
	v_mov_b32_e32 v21, v2
	v_mov_b32_e32 v26, v2
	v_mov_b32_e32 v27, v2
	v_mov_b32_e32 v28, v2
	v_mov_b32_e32 v29, v2
	v_mov_b32_e32 v34, v2
	v_mov_b32_e32 v35, v2
	v_mov_b32_e32 v36, v2
	v_mov_b32_e32 v37, v2
	v_mov_b32_e32 v42, v2
	v_mov_b32_e32 v43, v2
	v_mov_b32_e32 v44, v2
	v_mov_b32_e32 v45, v2
	v_mov_b32_e32 v50, v2
	v_mov_b32_e32 v51, v2
	v_mov_b32_e32 v52, v2
	v_mov_b32_e32 v53, v2
	v_mov_b32_e32 v58, v2
	v_mov_b32_e32 v59, v2
	v_mov_b32_e32 v60, v2
	v_mov_b32_e32 v61, v2
	v_mov_b32_e32 v6, v2
	v_mov_b32_e32 v7, v2
	v_mov_b32_e32 v8, v2
	v_mov_b32_e32 v9, v2
	v_mov_b32_e32 v14, v2
	v_mov_b32_e32 v15, v2
	v_mov_b32_e32 v16, v2
	v_mov_b32_e32 v17, v2
	v_mov_b32_e32 v22, v2
	v_mov_b32_e32 v23, v2
	v_mov_b32_e32 v24, v2
	v_mov_b32_e32 v25, v2
	v_mov_b32_e32 v30, v2
	v_mov_b32_e32 v31, v2
	v_mov_b32_e32 v32, v2
	v_mov_b32_e32 v33, v2
	v_mov_b32_e32 v38, v2
	v_mov_b32_e32 v39, v2
	v_mov_b32_e32 v40, v2
	v_mov_b32_e32 v41, v2
	v_mov_b32_e32 v46, v2
	v_mov_b32_e32 v47, v2
	v_mov_b32_e32 v48, v2
	v_mov_b32_e32 v49, v2
	v_mov_b32_e32 v54, v2
	v_mov_b32_e32 v55, v2
	v_mov_b32_e32 v56, v2
	v_mov_b32_e32 v57, v2
	v_mov_b32_e32 v62, v2
	v_mov_b32_e32 v63, v2
	v_mov_b32_e32 v64, v2
	v_mov_b32_e32 v65, v2
	v_mov_b32_e32 v66, v2
	v_mov_b32_e32 v67, v2
	v_mov_b32_e32 v68, v2
	v_mov_b32_e32 v69, v2
	v_mov_b32_e32 v74, v2
	v_mov_b32_e32 v75, v2
	v_mov_b32_e32 v76, v2
	v_mov_b32_e32 v77, v2
	v_mov_b32_e32 v86, v2
	v_mov_b32_e32 v87, v2
	v_mov_b32_e32 v88, v2
	v_mov_b32_e32 v89, v2
	v_mov_b32_e32 v94, v2
	v_mov_b32_e32 v95, v2
	v_mov_b32_e32 v96, v2
	v_mov_b32_e32 v97, v2
	v_mov_b32_e32 v106, v2
	v_mov_b32_e32 v107, v2
	v_mov_b32_e32 v108, v2
	v_mov_b32_e32 v109, v2
	v_mov_b32_e32 v114, v2
	v_mov_b32_e32 v115, v2
	v_mov_b32_e32 v116, v2
	v_mov_b32_e32 v117, v2
	v_mov_b32_e32 v124, v2
	v_mov_b32_e32 v125, v2
	v_mov_b32_e32 v126, v2
	v_mov_b32_e32 v127, v2
	v_mov_b32_e32 v82, v2
	v_mov_b32_e32 v83, v2
	v_mov_b32_e32 v84, v2
	v_mov_b32_e32 v85, v2
	v_mov_b32_e32 v70, v2
	v_mov_b32_e32 v71, v2
	v_mov_b32_e32 v72, v2
	v_mov_b32_e32 v73, v2
	v_mov_b32_e32 v78, v2
	v_mov_b32_e32 v79, v2
	v_mov_b32_e32 v80, v2
	v_mov_b32_e32 v81, v2
	v_mov_b32_e32 v90, v2
	v_mov_b32_e32 v91, v2
	v_mov_b32_e32 v92, v2
	v_mov_b32_e32 v93, v2
	v_mov_b32_e32 v98, v2
	v_mov_b32_e32 v99, v2
	v_mov_b32_e32 v100, v2
	v_mov_b32_e32 v101, v2
	v_mov_b32_e32 v110, v2
	v_mov_b32_e32 v111, v2
	v_mov_b32_e32 v112, v2
	v_mov_b32_e32 v113, v2
	v_mov_b32_e32 v118, v2
	v_mov_b32_e32 v119, v2
	v_mov_b32_e32 v120, v2
	v_mov_b32_e32 v121, v2
	v_mov_b32_e32 v128, v2
	v_mov_b32_e32 v129, v2
	v_mov_b32_e32 v130, v2
	v_mov_b32_e32 v131, v2
	v_mov_b32_e32 v136, v2
	v_mov_b32_e32 v137, v2
	v_mov_b32_e32 v138, v2
	v_mov_b32_e32 v139, v2
	v_readfirstlane_b32 s101, v242
	s_nop 3
	s_lshr_b32 s101, s101, 8
	s_cmp_eq_u32 s101, 0
	s_cbranch_scc0 .Lsp_1
	s_setprio 1

; template <class Epi>
; DI void gemm_phase(LAS unsigned char* lds, const Gemm g, const StaticOrder& S, const Epi& E) {
;     ...
;         for (int a = 0; a < 2; ++a)
; #pragma unroll
;             for (int b = 0; b < 2; ++b)
; #pragma unroll
;                 for (int m = 0; m < 4; ++m)
; #pragma unroll
;                     for (int n = 0; n < 2; ++n) acc[a][b][m][n] = (f32x4){0.f, 0.f, 0.f, 0.f};
.LBB0_782:
	s_add_u32 s73, s60, 0x100
	v_mov_b32_e32 v2, 0
	s_addc_u32 s91, s61, 0
	s_mov_b32 s93, -2
	v_mov_b32_e32 v3, v2
	v_mov_b32_e32 v4, v2
	v_mov_b32_e32 v5, v2
	v_mov_b32_e32 v6, v2
	v_mov_b32_e32 v7, v2
	v_mov_b32_e32 v8, v2
	v_mov_b32_e32 v9, v2
	v_mov_b32_e32 v18, v2
	v_mov_b32_e32 v19, v2
	v_mov_b32_e32 v20, v2
	v_mov_b32_e32 v21, v2
	v_mov_b32_e32 v22, v2
	v_mov_b32_e32 v23, v2
	v_mov_b32_e32 v24, v2
	v_mov_b32_e32 v25, v2
	v_mov_b32_e32 v34, v2
	v_mov_b32_e32 v35, v2
	v_mov_b32_e32 v36, v2
	v_mov_b32_e32 v37, v2
	v_mov_b32_e32 v38, v2
	v_mov_b32_e32 v39, v2
	v_mov_b32_e32 v40, v2
	v_mov_b32_e32 v41, v2
	v_mov_b32_e32 v50, v2
	v_mov_b32_e32 v51, v2
	v_mov_b32_e32 v52, v2
	v_mov_b32_e32 v53, v2
	v_mov_b32_e32 v54, v2
	v_mov_b32_e32 v55, v2
	v_mov_b32_e32 v56, v2
	v_mov_b32_e32 v57, v2
	v_mov_b32_e32 v10, v2
	v_mov_b32_e32 v11, v2
	v_mov_b32_e32 v12, v2
	v_mov_b32_e32 v13, v2
	v_mov_b32_e32 v14, v2
	v_mov_b32_e32 v15, v2
	v_mov_b32_e32 v16, v2
	v_mov_b32_e32 v17, v2
	v_mov_b32_e32 v26, v2
	v_mov_b32_e32 v27, v2
	v_mov_b32_e32 v28, v2
	v_mov_b32_e32 v29, v2
	v_mov_b32_e32 v30, v2
	v_mov_b32_e32 v31, v2
	v_mov_b32_e32 v32, v2
	v_mov_b32_e32 v33, v2
	v_mov_b32_e32 v42, v2
	v_mov_b32_e32 v43, v2
	v_mov_b32_e32 v44, v2
	v_mov_b32_e32 v45, v2
	v_mov_b32_e32 v46, v2
	v_mov_b32_e32 v47, v2
	v_mov_b32_e32 v48, v2
	v_mov_b32_e32 v49, v2
	v_mov_b32_e32 v58, v2
	v_mov_b32_e32 v59, v2
	v_mov_b32_e32 v60, v2
	v_mov_b32_e32 v61, v2
	v_mov_b32_e32 v62, v2
	v_mov_b32_e32 v63, v2
	v_mov_b32_e32 v64, v2
	v_mov_b32_e32 v65, v2
	v_mov_b32_e32 v66, v2
	v_mov_b32_e32 v67, v2
	v_mov_b32_e32 v68, v2
	v_mov_b32_e32 v69, v2
	v_mov_b32_e32 v70, v2
	v_mov_b32_e32 v71, v2
	v_mov_b32_e32 v72, v2
	v_mov_b32_e32 v73, v2
	v_mov_b32_e32 v82, v2
	v_mov_b32_e32 v83, v2
	v_mov_b32_e32 v84, v2
	v_mov_b32_e32 v85, v2
	v_mov_b32_e32 v86, v2
	v_mov_b32_e32 v87, v2
	v_mov_b32_e32 v88, v2
	v_mov_b32_e32 v89, v2
	v_mov_b32_e32 v98, v2
	v_mov_b32_e32 v99, v2
	v_mov_b32_e32 v100, v2
	v_mov_b32_e32 v101, v2
	v_mov_b32_e32 v102, v2
	v_mov_b32_e32 v103, v2
	v_mov_b32_e32 v104, v2
	v_mov_b32_e32 v105, v2
	v_mov_b32_e32 v130, v2
	v_mov_b32_e32 v131, v2
	v_mov_b32_e32 v132, v2
	v_mov_b32_e32 v133, v2
	v_mov_b32_e32 v142, v2
	v_mov_b32_e32 v143, v2
	v_mov_b32_e32 v144, v2
	v_mov_b32_e32 v145, v2
	v_mov_b32_e32 v74, v2
	v_mov_b32_e32 v75, v2
	v_mov_b32_e32 v76, v2
	v_mov_b32_e32 v77, v2
	v_mov_b32_e32 v78, v2
	v_mov_b32_e32 v79, v2
	v_mov_b32_e32 v80, v2
	v_mov_b32_e32 v81, v2
	v_mov_b32_e32 v90, v2
	v_mov_b32_e32 v91, v2
	v_mov_b32_e32 v92, v2
	v_mov_b32_e32 v93, v2
	v_mov_b32_e32 v94, v2
	v_mov_b32_e32 v95, v2
	v_mov_b32_e32 v96, v2
	v_mov_b32_e32 v97, v2
	v_mov_b32_e32 v106, v2
	v_mov_b32_e32 v107, v2
	v_mov_b32_e32 v108, v2
	v_mov_b32_e32 v109, v2
	v_mov_b32_e32 v110, v2
	v_mov_b32_e32 v111, v2
	v_mov_b32_e32 v112, v2
	v_mov_b32_e32 v113, v2
	v_mov_b32_e32 v150, v2
	v_mov_b32_e32 v151, v2
	v_mov_b32_e32 v152, v2
	v_mov_b32_e32 v153, v2
	v_mov_b32_e32 v158, v2
	v_mov_b32_e32 v159, v2
	v_mov_b32_e32 v160, v2
	v_mov_b32_e32 v161, v2
	v_readfirstlane_b32 s101, v242
	s_nop 3
	s_lshr_b32 s101, s101, 8
	s_cmp_eq_u32 s101, 0
	s_cbranch_scc0 .Lsp_0
	s_setprio 1
